# adds per-XCD rotation of the P5 conv item order (decorrelates the 8 XCDs' streams through the batch-aligned U tensor)
# baseline (speedup 1.0000x reference)
.LBB0_425:
	s_cmp_lt_i32 s30, 6
	s_cselect_b64 s[2:3], -1, 0
	s_add_u32 s4, s28, 0x15000000
	v_writelane_b32 v254, s4, 58
	s_addc_u32 s4, s29, 0
	s_and_b64 s[26:27], s[2:3], s[0:1]
	v_writelane_b32 v254, s4, 61
	s_andn2_b64 vcc, exec, s[26:27]
	s_cbranch_vccnz .LBB0_518
	s_lshl_b32 s16, s18, 7
	s_and_b32 s8, s16, 0x180
	s_waitcnt vmcnt(0)
	v_mbcnt_lo_u32_b32 v140, -1, 0
	v_mbcnt_hi_u32_b32 v140, -1, v140
	v_readlane_b32 s60, v254, 15
	v_lshlrev_b32_e32 v106, 1, v140
	v_add_u32_e32 v104, s8, v106
	v_ashrrev_i32_e32 v105, 31, v104
	s_waitcnt lgkmcnt(0)
	v_lshlrev_b64 v[2:3], 2, v[104:105]
	v_readlane_b32 s62, v254, 17
	v_readlane_b32 s63, v254, 18
	s_movk_i32 s0, 0x1000
	v_readlane_b32 s64, v254, 19
	v_lshl_add_u64 v[4:5], s[62:63], 0, v[2:3]
	v_add_co_u32_e32 v6, vcc, s0, v4
	s_movk_i32 s0, 0x2000
	s_nop 0
	v_addc_co_u32_e32 v7, vcc, 0, v5, vcc
	v_add_co_u32_e32 v8, vcc, s0, v4
	s_movk_i32 s0, 0x3000
	s_nop 0
	v_addc_co_u32_e32 v9, vcc, 0, v5, vcc
	v_add_co_u32_e32 v10, vcc, s0, v4
	s_movk_i32 s0, 0x4000
	s_nop 0
	v_addc_co_u32_e32 v11, vcc, 0, v5, vcc
	v_add_co_u32_e32 v12, vcc, s0, v4
	s_movk_i32 s0, 0x5000
	s_nop 0
	v_addc_co_u32_e32 v13, vcc, 0, v5, vcc
	global_load_dwordx2 v[34:35], v[8:9], off offset:-4096
	global_load_dwordx2 v[36:37], v[8:9], off
	global_load_dwordx2 v[38:39], v[8:9], off offset:2048
	global_load_dwordx2 v[40:41], v[12:13], off offset:-4096
	global_load_dwordx2 v[42:43], v[4:5], off
	global_load_dwordx2 v[44:45], v[4:5], off offset:2048
	global_load_dwordx2 v[46:47], v[6:7], off offset:2048
	global_load_dwordx2 v[48:49], v[10:11], off offset:2048
	v_add_co_u32_e32 v6, vcc, s0, v4
	s_movk_i32 s0, 0x6000
	s_nop 0
	v_addc_co_u32_e32 v7, vcc, 0, v5, vcc
	v_add_co_u32_e32 v8, vcc, s0, v4
	s_movk_i32 s0, 0x7000
	s_nop 0
	v_addc_co_u32_e32 v9, vcc, 0, v5, vcc
	v_add_co_u32_e32 v10, vcc, s0, v4
	s_mov_b32 s0, 0x8000
	s_nop 0
	v_addc_co_u32_e32 v11, vcc, 0, v5, vcc
	global_load_dwordx2 v[50:51], v[12:13], off
	global_load_dwordx2 v[52:53], v[12:13], off offset:2048
	global_load_dwordx2 v[54:55], v[8:9], off offset:-4096
	global_load_dwordx2 v[56:57], v[8:9], off
	v_add_co_u32_e32 v12, vcc, s0, v4
	s_mov_b32 s0, 0x9000
	s_nop 0
	v_addc_co_u32_e32 v13, vcc, 0, v5, vcc
	global_load_dwordx2 v[58:59], v[8:9], off offset:2048
	global_load_dwordx2 v[60:61], v[12:13], off offset:-4096
	global_load_dwordx2 v[62:63], v[12:13], off
	global_load_dwordx2 v[64:65], v[12:13], off offset:2048
	v_add_co_u32_e32 v8, vcc, s0, v4
	s_mov_b32 s0, 0xa000
	s_nop 0
	v_addc_co_u32_e32 v9, vcc, 0, v5, vcc
	v_add_co_u32_e32 v12, vcc, s0, v4
	s_mov_b32 s0, 0xb000
	s_nop 0
	v_addc_co_u32_e32 v13, vcc, 0, v5, vcc
	v_add_co_u32_e32 v14, vcc, s0, v4
	s_mov_b32 s0, 0xc000
	s_nop 0
	v_addc_co_u32_e32 v15, vcc, 0, v5, vcc
	v_add_co_u32_e32 v16, vcc, s0, v4
	s_mov_b32 s0, 0xd000
	s_nop 0
	v_addc_co_u32_e32 v17, vcc, 0, v5, vcc
	global_load_dwordx2 v[66:67], v[12:13], off offset:-4096
	global_load_dwordx2 v[68:69], v[12:13], off
	global_load_dwordx2 v[70:71], v[12:13], off offset:2048
	global_load_dwordx2 v[72:73], v[16:17], off offset:-4096
	global_load_dwordx2 v[74:75], v[6:7], off offset:2048
	global_load_dwordx2 v[76:77], v[10:11], off offset:2048
	global_load_dwordx2 v[78:79], v[8:9], off offset:2048
	global_load_dwordx2 v[80:81], v[14:15], off offset:2048
	v_add_co_u32_e32 v6, vcc, s0, v4
	s_mov_b32 s0, 0xe000
	s_nop 0
	v_addc_co_u32_e32 v7, vcc, 0, v5, vcc
	v_add_co_u32_e32 v8, vcc, s0, v4
	v_readlane_b32 s65, v254, 20
	s_nop 0
	v_addc_co_u32_e32 v9, vcc, 0, v5, vcc
	v_add_co_u32_e32 v4, vcc, 0xf000, v4
	global_load_dwordx2 v[82:83], v[16:17], off
	global_load_dwordx2 v[84:85], v[16:17], off offset:2048
	global_load_dwordx2 v[86:87], v[8:9], off offset:-4096
	global_load_dwordx2 v[88:89], v[8:9], off
	global_load_dwordx2 v[90:91], v[8:9], off offset:2048
	v_addc_co_u32_e32 v5, vcc, 0, v5, vcc
	v_readlane_b32 s66, v254, 21
	v_readlane_b32 s67, v254, 22
	v_readlane_b32 s68, v254, 23
	v_readlane_b32 s69, v254, 24
	global_load_dwordx2 v[92:93], v[6:7], off offset:2048
	global_load_dwordx2 v[94:95], v[4:5], off
	v_lshl_add_u64 v[4:5], s[64:65], 0, v[2:3]
	global_load_dwordx2 v[96:97], v[4:5], off
	v_lshl_add_u64 v[4:5], s[66:67], 0, v[2:3]
	v_lshl_add_u64 v[2:3], s[68:69], 0, v[2:3]
	global_load_dwordx2 v[98:99], v[4:5], off
	global_load_dwordx2 v[100:101], v[2:3], off
	s_add_u32 s98, s28, 0xf000000
	s_addc_u32 s99, s29, 0
	s_lshl_b32 s17, s24, 5
	s_cmp_eq_u32 s25, 0x100
	s_cbranch_scc0 .Lp5_noremap_a
	s_and_b32 s17, s24, 7
	s_lshl_b32 s17, s17, 12
	s_lshr_b32 s0, s24, 3
	s_lshl_b32 s0, s0, 5
	s_add_i32 s17, s17, s0
	s_and_b32 s0, s24, 3
	s_lshl_b32 s0, s0, 10
	s_add_i32 s17, s17, s0

.LBB0_445:
	s_barrier
	s_waitcnt vmcnt(0)
	ds_write_b128 v151, v[6:9]
	ds_write_b128 v152, v[2:5]
	ds_write_b128 v153, v[14:17]
	ds_write_b128 v154, v[10:13]
	ds_write_b128 v155, v[22:25]
	ds_write_b128 v156, v[18:21]
	s_and_saveexec_b64 s[0:1], s[2:3]
	ds_write_b128 v157, v[30:33]
	s_or_b64 exec, exec, s[0:1]
	s_and_saveexec_b64 s[0:1], s[4:5]
	ds_write_b128 v158, v[26:29]
	s_or_b64 exec, exec, s[0:1]
	s_add_i32 s59, s33, s17
	s_cmp_eq_u32 s25, 0x100
	s_cbranch_scc0 .Lp5_nowrap
	s_and_b32 s59, s59, 0xfff
	s_and_b32 s98, s17, 0xfffff000
	s_or_b32 s59, s59, s98
.Lp5_nowrap:
	s_and_b32 s0, s59, 0xfe0
	s_add_i32 s58, s58, s25
	s_sub_i32 s60, s0, 30
	s_cmpk_lt_i32 s58, 0x400
	v_add_u32_e32 v3, s60, v1
	s_cselect_b64 s[52:53], -1, 0
	s_cmpk_gt_i32 s58, 0x3ff
	v_cmp_lt_i32_e32 vcc, -1, v3
	s_cselect_b64 s[50:51], -1, 0
	s_and_b32 s61, s59, 0xfffff000
	s_and_b64 s[34:35], s[52:53], vcc
	v_mov_b32_e32 v2, 0
	v_mov_b32_e32 v6, 0
	v_mov_b32_e32 v7, 0
	v_mov_b32_e32 v8, 0
	v_mov_b32_e32 v9, 0
	s_and_saveexec_b64 s[0:1], s[34:35]
	s_cbranch_execz .LBB0_451
	v_add_u32_e32 v4, s61, v3
	v_ashrrev_i32_e32 v5, 31, v4
	v_lshlrev_b64 v[4:5], 10, v[4:5]
	v_lshl_add_u64 v[4:5], v[102:103], 0, v[4:5]
	global_load_dwordx4 v[6:9], v[4:5], off
